# accumulator clearing per unit: 64 x v_mov_b64 0 instead of 128 x v_mov_b32 (10 GEMM phases)
# baseline (speedup 1.0000x reference)
;     ...
;         if (!(cs.kind == K_MG_B && cur.aux < 2))
; #pragma unroll
;         for (int a = 0; a < 2; ++a)
; #pragma unroll
;             for (int b = 0; b < 2; ++b)
; #pragma unroll
;                 for (int m = 0; m < 4; ++m)
; #pragma unroll
;                     for (int n = 0; n < 2; ++n) acc[a][b][m][n] = (f32x4){0.f, 0.f, 0.f, 0.f};
;         cur = nxt; cA = nA; cB = nB; ++ui;
.LBB0_211:
	s_add_u32 s2, s2, 0x40080
	s_addc_u32 s3, s3, 0
	s_add_u32 s7, s22, 0x100
	v_mov_b64_e32 v[8:9], 0
	s_addc_u32 s22, s23, 0
	s_mov_b32 s23, -2
	v_mov_b64_e32 v[10:11], 0
	v_mov_b64_e32 v[12:13], 0
	v_mov_b64_e32 v[14:15], 0
	v_mov_b64_e32 v[24:25], 0
	v_mov_b64_e32 v[26:27], 0
	v_mov_b64_e32 v[28:29], 0
	v_mov_b64_e32 v[30:31], 0
	v_mov_b64_e32 v[40:41], 0
	v_mov_b64_e32 v[42:43], 0
	v_mov_b64_e32 v[44:45], 0
	v_mov_b64_e32 v[46:47], 0
	v_mov_b64_e32 v[56:57], 0
	v_mov_b64_e32 v[58:59], 0
	v_mov_b64_e32 v[60:61], 0
	v_mov_b64_e32 v[62:63], 0
	v_mov_b64_e32 v[16:17], 0
	v_mov_b64_e32 v[18:19], 0
	v_mov_b64_e32 v[20:21], 0
	v_mov_b64_e32 v[22:23], 0
	v_mov_b64_e32 v[32:33], 0
	v_mov_b64_e32 v[34:35], 0
	v_mov_b64_e32 v[36:37], 0
	v_mov_b64_e32 v[38:39], 0
	v_mov_b64_e32 v[48:49], 0
	v_mov_b64_e32 v[50:51], 0
	v_mov_b64_e32 v[52:53], 0
	v_mov_b64_e32 v[54:55], 0
	v_mov_b64_e32 v[64:65], 0
	v_mov_b64_e32 v[66:67], 0
	v_mov_b64_e32 v[68:69], 0
	v_mov_b64_e32 v[70:71], 0
	v_mov_b64_e32 v[72:73], 0
	v_mov_b64_e32 v[74:75], 0
	v_mov_b64_e32 v[76:77], 0
	v_mov_b64_e32 v[78:79], 0
	v_mov_b64_e32 v[88:89], 0
	v_mov_b64_e32 v[90:91], 0
	v_mov_b64_e32 v[92:93], 0
	v_mov_b64_e32 v[94:95], 0
	v_mov_b64_e32 v[104:105], 0
	v_mov_b64_e32 v[106:107], 0
	v_mov_b64_e32 v[108:109], 0
	v_mov_b64_e32 v[110:111], 0
	v_mov_b64_e32 v[120:121], 0
	v_mov_b64_e32 v[122:123], 0
	v_mov_b64_e32 v[124:125], 0
	v_mov_b64_e32 v[126:127], 0
	v_mov_b64_e32 v[80:81], 0
	v_mov_b64_e32 v[82:83], 0
	v_mov_b64_e32 v[84:85], 0
	v_mov_b64_e32 v[86:87], 0
	v_mov_b64_e32 v[96:97], 0
	v_mov_b64_e32 v[98:99], 0
	v_mov_b64_e32 v[100:101], 0
	v_mov_b64_e32 v[102:103], 0
	v_mov_b64_e32 v[112:113], 0
	v_mov_b64_e32 v[114:115], 0
	v_mov_b64_e32 v[116:117], 0
	v_mov_b64_e32 v[118:119], 0
	v_mov_b64_e32 v[128:129], 0
	v_mov_b64_e32 v[130:131], 0
	v_mov_b64_e32 v[132:133], 0
	v_mov_b64_e32 v[134:135], 0
	s_mov_b64 s[52:53], 0x40000
	s_mov_b64 s[54:55], 0x60000
	s_mov_b64 s[58:59], 0x20080
	s_mov_b64 s[62:63], 0x40080
	s_mov_b64 s[64:65], 0x60080

;     ...
;         if (!(cs.kind == K_MG_B && cur.aux < 2))
; #pragma unroll
;         for (int a = 0; a < 2; ++a)
; #pragma unroll
;             for (int b = 0; b < 2; ++b)
; #pragma unroll
;                 for (int m = 0; m < 4; ++m)
; #pragma unroll
;                     for (int n = 0; n < 2; ++n) acc[a][b][m][n] = (f32x4){0.f, 0.f, 0.f, 0.f};
;         cur = nxt; cA = nA; cB = nB; ++ui;
.LBB0_449:
	s_add_u32 s6, s22, 0x20080
	s_addc_u32 s7, s23, 0
	s_add_u32 s19, s20, 0x100
	v_mov_b64_e32 v[8:9], 0
	s_addc_u32 s20, s21, 0
	s_mov_b32 s21, -2
	v_mov_b64_e32 v[10:11], 0
	v_mov_b64_e32 v[12:13], 0
	v_mov_b64_e32 v[14:15], 0
	v_mov_b64_e32 v[24:25], 0
	v_mov_b64_e32 v[26:27], 0
	v_mov_b64_e32 v[28:29], 0
	v_mov_b64_e32 v[30:31], 0
	v_mov_b64_e32 v[40:41], 0
	v_mov_b64_e32 v[42:43], 0
	v_mov_b64_e32 v[44:45], 0
	v_mov_b64_e32 v[46:47], 0
	v_mov_b64_e32 v[56:57], 0
	v_mov_b64_e32 v[58:59], 0
	v_mov_b64_e32 v[60:61], 0
	v_mov_b64_e32 v[62:63], 0
	v_mov_b64_e32 v[16:17], 0
	v_mov_b64_e32 v[18:19], 0
	v_mov_b64_e32 v[20:21], 0
	v_mov_b64_e32 v[22:23], 0
	v_mov_b64_e32 v[32:33], 0
	v_mov_b64_e32 v[34:35], 0
	v_mov_b64_e32 v[36:37], 0
	v_mov_b64_e32 v[38:39], 0
	v_mov_b64_e32 v[48:49], 0
	v_mov_b64_e32 v[50:51], 0
	v_mov_b64_e32 v[52:53], 0
	v_mov_b64_e32 v[54:55], 0
	v_mov_b64_e32 v[64:65], 0
	v_mov_b64_e32 v[66:67], 0
	v_mov_b64_e32 v[68:69], 0
	v_mov_b64_e32 v[70:71], 0
	v_mov_b64_e32 v[72:73], 0
	v_mov_b64_e32 v[74:75], 0
	v_mov_b64_e32 v[76:77], 0
	v_mov_b64_e32 v[78:79], 0
	v_mov_b64_e32 v[88:89], 0
	v_mov_b64_e32 v[90:91], 0
	v_mov_b64_e32 v[92:93], 0
	v_mov_b64_e32 v[94:95], 0
	v_mov_b64_e32 v[104:105], 0
	v_mov_b64_e32 v[106:107], 0
	v_mov_b64_e32 v[108:109], 0
	v_mov_b64_e32 v[110:111], 0
	v_mov_b64_e32 v[120:121], 0
	v_mov_b64_e32 v[122:123], 0
	v_mov_b64_e32 v[124:125], 0
	v_mov_b64_e32 v[126:127], 0
	v_mov_b64_e32 v[80:81], 0
	v_mov_b64_e32 v[82:83], 0
	v_mov_b64_e32 v[84:85], 0
	v_mov_b64_e32 v[86:87], 0
	v_mov_b64_e32 v[96:97], 0
	v_mov_b64_e32 v[98:99], 0
	v_mov_b64_e32 v[100:101], 0
	v_mov_b64_e32 v[102:103], 0
	v_mov_b64_e32 v[112:113], 0
	v_mov_b64_e32 v[114:115], 0
	v_mov_b64_e32 v[116:117], 0
	v_mov_b64_e32 v[118:119], 0
	v_mov_b64_e32 v[128:129], 0
	v_mov_b64_e32 v[130:131], 0
	v_mov_b64_e32 v[132:133], 0
	v_mov_b64_e32 v[134:135], 0
	s_mov_b64 s[50:51], 0x20080
	s_mov_b64 s[52:53], 0x10000
	s_mov_b64 s[54:55], 0x30000
	s_mov_b64 s[58:59], 0x10080
	s_mov_b64 s[62:63], 0x30080

;     ...
;         if (!(cs.kind == K_MG_B && cur.aux < 2))
; #pragma unroll
;         for (int a = 0; a < 2; ++a)
; #pragma unroll
;             for (int b = 0; b < 2; ++b)
; #pragma unroll
;                 for (int m = 0; m < 4; ++m)
; #pragma unroll
;                     for (int n = 0; n < 2; ++n) acc[a][b][m][n] = (f32x4){0.f, 0.f, 0.f, 0.f};
;         cur = nxt; cA = nA; cB = nB; ++ui;
.LBB0_741:
	v_mov_b64_e32 v[8:9], 0
	s_mov_b64 s[30:31], 0
	s_mov_b64 s[24:25], -1
	s_mov_b64 s[26:27], 0
	v_mov_b64_e32 v[10:11], 0
	v_mov_b64_e32 v[12:13], 0
	v_mov_b64_e32 v[14:15], 0
	v_mov_b64_e32 v[24:25], 0
	v_mov_b64_e32 v[26:27], 0
	v_mov_b64_e32 v[28:29], 0
	v_mov_b64_e32 v[30:31], 0
	v_mov_b64_e32 v[40:41], 0
	v_mov_b64_e32 v[42:43], 0
	v_mov_b64_e32 v[44:45], 0
	v_mov_b64_e32 v[46:47], 0
	v_mov_b64_e32 v[64:65], 0
	v_mov_b64_e32 v[66:67], 0
	v_mov_b64_e32 v[68:69], 0
	v_mov_b64_e32 v[70:71], 0
	v_mov_b64_e32 v[16:17], 0
	v_mov_b64_e32 v[18:19], 0
	v_mov_b64_e32 v[20:21], 0
	v_mov_b64_e32 v[22:23], 0
	v_mov_b64_e32 v[32:33], 0
	v_mov_b64_e32 v[34:35], 0
	v_mov_b64_e32 v[36:37], 0
	v_mov_b64_e32 v[38:39], 0
	v_mov_b64_e32 v[48:49], 0
	v_mov_b64_e32 v[50:51], 0
	v_mov_b64_e32 v[52:53], 0
	v_mov_b64_e32 v[54:55], 0
	v_mov_b64_e32 v[72:73], 0
	v_mov_b64_e32 v[74:75], 0
	v_mov_b64_e32 v[76:77], 0
	v_mov_b64_e32 v[78:79], 0
	v_mov_b64_e32 v[80:81], 0
	v_mov_b64_e32 v[82:83], 0
	v_mov_b64_e32 v[84:85], 0
	v_mov_b64_e32 v[86:87], 0
	v_mov_b64_e32 v[96:97], 0
	v_mov_b64_e32 v[98:99], 0
	v_mov_b64_e32 v[100:101], 0
	v_mov_b64_e32 v[102:103], 0
	v_mov_b64_e32 v[112:113], 0
	v_mov_b64_e32 v[114:115], 0
	v_mov_b64_e32 v[116:117], 0
	v_mov_b64_e32 v[118:119], 0
	v_mov_b64_e32 v[128:129], 0
	v_mov_b64_e32 v[130:131], 0
	v_mov_b64_e32 v[132:133], 0
	v_mov_b64_e32 v[134:135], 0
	v_mov_b64_e32 v[88:89], 0
	v_mov_b64_e32 v[90:91], 0
	v_mov_b64_e32 v[92:93], 0
	v_mov_b64_e32 v[94:95], 0
	v_mov_b64_e32 v[104:105], 0
	v_mov_b64_e32 v[106:107], 0
	v_mov_b64_e32 v[108:109], 0
	v_mov_b64_e32 v[110:111], 0
	v_mov_b64_e32 v[120:121], 0
	v_mov_b64_e32 v[122:123], 0
	v_mov_b64_e32 v[124:125], 0
	v_mov_b64_e32 v[126:127], 0
	v_mov_b64_e32 v[136:137], 0
	v_mov_b64_e32 v[138:139], 0
	v_mov_b64_e32 v[140:141], 0
	v_mov_b64_e32 v[142:143], 0
	s_mov_b64 s[82:83], 0x10000
	s_mov_b64 s[84:85], 0x10080
	s_mov_b64 s[86:87], 0x200000
	s_mov_b64 s[88:89], 0x100000
	s_mov_b64 s[92:93], 0x8000
	s_mov_b64 s[94:95], 0x18000
	s_mov_b64 s[96:97], 0x300000
	s_mov_b64 s[70:71], 0x8080
	s_mov_b64 s[68:69], 0x100080
	s_mov_b64 s[28:29], 0x18080

;     ...
;         if (!(cs.kind == K_MG_B && cur.aux < 2))
; #pragma unroll
;         for (int a = 0; a < 2; ++a)
; #pragma unroll
;             for (int b = 0; b < 2; ++b)
; #pragma unroll
;                 for (int m = 0; m < 4; ++m)
; #pragma unroll
;                     for (int n = 0; n < 2; ++n) acc[a][b][m][n] = (f32x4){0.f, 0.f, 0.f, 0.f};
;         cur = nxt; cA = nA; cB = nB; ++ui;
.LBB0_803:
	s_add_u32 s13, s18, 0x100
	s_addc_u32 s18, s19, 0
	s_add_u32 s2, s2, 0x800000
	v_mov_b64_e32 v[8:9], 0
	s_addc_u32 s3, s3, 0
	s_mov_b32 s19, -2
	v_mov_b64_e32 v[10:11], 0
	v_mov_b64_e32 v[12:13], 0
	v_mov_b64_e32 v[14:15], 0
	v_mov_b64_e32 v[24:25], 0
	v_mov_b64_e32 v[26:27], 0
	v_mov_b64_e32 v[28:29], 0
	v_mov_b64_e32 v[30:31], 0
	v_mov_b64_e32 v[40:41], 0
	v_mov_b64_e32 v[42:43], 0
	v_mov_b64_e32 v[44:45], 0
	v_mov_b64_e32 v[46:47], 0
	v_mov_b64_e32 v[56:57], 0
	v_mov_b64_e32 v[58:59], 0
	v_mov_b64_e32 v[60:61], 0
	v_mov_b64_e32 v[62:63], 0
	v_mov_b64_e32 v[16:17], 0
	v_mov_b64_e32 v[18:19], 0
	v_mov_b64_e32 v[20:21], 0
	v_mov_b64_e32 v[22:23], 0
	v_mov_b64_e32 v[32:33], 0
	v_mov_b64_e32 v[34:35], 0
	v_mov_b64_e32 v[36:37], 0
	v_mov_b64_e32 v[38:39], 0
	v_mov_b64_e32 v[48:49], 0
	v_mov_b64_e32 v[50:51], 0
	v_mov_b64_e32 v[52:53], 0
	v_mov_b64_e32 v[54:55], 0
	v_mov_b64_e32 v[64:65], 0
	v_mov_b64_e32 v[66:67], 0
	v_mov_b64_e32 v[68:69], 0
	v_mov_b64_e32 v[70:71], 0
	v_mov_b64_e32 v[72:73], 0
	v_mov_b64_e32 v[74:75], 0
	v_mov_b64_e32 v[76:77], 0
	v_mov_b64_e32 v[78:79], 0
	v_mov_b64_e32 v[88:89], 0
	v_mov_b64_e32 v[90:91], 0
	v_mov_b64_e32 v[92:93], 0
	v_mov_b64_e32 v[94:95], 0
	v_mov_b64_e32 v[104:105], 0
	v_mov_b64_e32 v[106:107], 0
	v_mov_b64_e32 v[108:109], 0
	v_mov_b64_e32 v[110:111], 0
	v_mov_b64_e32 v[128:129], 0
	v_mov_b64_e32 v[130:131], 0
	v_mov_b64_e32 v[132:133], 0
	v_mov_b64_e32 v[134:135], 0
	v_mov_b64_e32 v[80:81], 0
	v_mov_b64_e32 v[82:83], 0
	v_mov_b64_e32 v[84:85], 0
	v_mov_b64_e32 v[86:87], 0
	v_mov_b64_e32 v[96:97], 0
	v_mov_b64_e32 v[98:99], 0
	v_mov_b64_e32 v[100:101], 0
	v_mov_b64_e32 v[102:103], 0
	v_mov_b64_e32 v[116:117], 0
	v_mov_b64_e32 v[118:119], 0
	v_mov_b64_e32 v[120:121], 0
	v_mov_b64_e32 v[122:123], 0
	v_mov_b64_e32 v[140:141], 0
	v_mov_b64_e32 v[142:143], 0
	v_mov_b64_e32 v[144:145], 0
	v_mov_b64_e32 v[146:147], 0
	s_mov_b64 s[42:43], 0x20080
	s_mov_b64 s[50:51], 0x10000
	s_mov_b64 s[52:53], 0x30000
	s_mov_b64 s[54:55], 0x10080
	s_mov_b64 s[58:59], 0x30080
	s_mov_b64 s[62:63], 0x400000

;     ...
;         if (!(cs.kind == K_MG_B && cur.aux < 2))
; #pragma unroll
;         for (int a = 0; a < 2; ++a)
; #pragma unroll
;             for (int b = 0; b < 2; ++b)
; #pragma unroll
;                 for (int m = 0; m < 4; ++m)
; #pragma unroll
;                     for (int n = 0; n < 2; ++n) acc[a][b][m][n] = (f32x4){0.f, 0.f, 0.f, 0.f};
;         cur = nxt; cA = nA; cB = nB; ++ui;
.LBB0_871:
	s_add_u32 s2, s2, 0xb0080
	s_addc_u32 s3, s3, 0
	s_add_u32 s37, s12, 0x100
	v_mov_b64_e32 v[8:9], 0
	s_addc_u32 s38, s13, 0
	s_mov_b32 s39, -2
	v_mov_b64_e32 v[10:11], 0
	v_mov_b64_e32 v[12:13], 0
	v_mov_b64_e32 v[14:15], 0
	v_mov_b64_e32 v[24:25], 0
	v_mov_b64_e32 v[26:27], 0
	v_mov_b64_e32 v[28:29], 0
	v_mov_b64_e32 v[30:31], 0
	v_mov_b64_e32 v[40:41], 0
	v_mov_b64_e32 v[42:43], 0
	v_mov_b64_e32 v[44:45], 0
	v_mov_b64_e32 v[46:47], 0
	v_mov_b64_e32 v[56:57], 0
	v_mov_b64_e32 v[58:59], 0
	v_mov_b64_e32 v[60:61], 0
	v_mov_b64_e32 v[62:63], 0
	v_mov_b64_e32 v[16:17], 0
	v_mov_b64_e32 v[18:19], 0
	v_mov_b64_e32 v[20:21], 0
	v_mov_b64_e32 v[22:23], 0
	v_mov_b64_e32 v[36:37], 0
	v_mov_b64_e32 v[38:39], 0
	v_mov_b64_e32 v[32:33], 0
	v_mov_b64_e32 v[34:35], 0
	v_mov_b64_e32 v[52:53], 0
	v_mov_b64_e32 v[54:55], 0
	v_mov_b64_e32 v[48:49], 0
	v_mov_b64_e32 v[50:51], 0
	v_mov_b64_e32 v[68:69], 0
	v_mov_b64_e32 v[70:71], 0
	v_mov_b64_e32 v[64:65], 0
	v_mov_b64_e32 v[66:67], 0
	v_mov_b64_e32 v[72:73], 0
	v_mov_b64_e32 v[74:75], 0
	v_mov_b64_e32 v[76:77], 0
	v_mov_b64_e32 v[78:79], 0
	v_mov_b64_e32 v[88:89], 0
	v_mov_b64_e32 v[90:91], 0
	v_mov_b64_e32 v[92:93], 0
	v_mov_b64_e32 v[94:95], 0
	v_mov_b64_e32 v[104:105], 0
	v_mov_b64_e32 v[106:107], 0
	v_mov_b64_e32 v[108:109], 0
	v_mov_b64_e32 v[110:111], 0
	v_mov_b64_e32 v[120:121], 0
	v_mov_b64_e32 v[122:123], 0
	v_mov_b64_e32 v[124:125], 0
	v_mov_b64_e32 v[126:127], 0
	v_mov_b64_e32 v[84:85], 0
	v_mov_b64_e32 v[86:87], 0
	v_mov_b64_e32 v[80:81], 0
	v_mov_b64_e32 v[82:83], 0
	v_mov_b64_e32 v[100:101], 0
	v_mov_b64_e32 v[102:103], 0
	v_mov_b64_e32 v[96:97], 0
	v_mov_b64_e32 v[98:99], 0
	v_mov_b64_e32 v[116:117], 0
	v_mov_b64_e32 v[118:119], 0
	v_mov_b64_e32 v[112:113], 0
	v_mov_b64_e32 v[114:115], 0
	v_mov_b64_e32 v[132:133], 0
	v_mov_b64_e32 v[134:135], 0
	v_mov_b64_e32 v[128:129], 0
	v_mov_b64_e32 v[130:131], 0
	s_mov_b64 s[42:43], 0x20080
	s_mov_b64 s[50:51], 0x10000
	s_mov_b64 s[52:53], 0x30000
	s_mov_b64 s[54:55], 0x10080
	s_mov_b64 s[58:59], 0x30080

;     ...
;         if (!(cs.kind == K_MG_B && cur.aux < 2))
; #pragma unroll
;         for (int a = 0; a < 2; ++a)
; #pragma unroll
;             for (int b = 0; b < 2; ++b)
; #pragma unroll
;                 for (int m = 0; m < 4; ++m)
; #pragma unroll
;                     for (int n = 0; n < 2; ++n) acc[a][b][m][n] = (f32x4){0.f, 0.f, 0.f, 0.f};
;         cur = nxt; cA = nA; cB = nB; ++ui;
.LBB0_1036:
	s_add_u32 s2, s2, 0x40080
	s_addc_u32 s3, s3, 0
	s_add_u32 s6, s6, 0x100
	s_waitcnt lgkmcnt(0)
	v_mov_b64_e32 v[8:9], 0
	s_addc_u32 s7, s7, 0
	s_mov_b32 s15, -2
	v_mov_b64_e32 v[10:11], 0
	v_mov_b64_e32 v[12:13], 0
	v_mov_b64_e32 v[14:15], 0
	v_mov_b64_e32 v[24:25], 0
	v_mov_b64_e32 v[26:27], 0
	v_mov_b64_e32 v[28:29], 0
	v_mov_b64_e32 v[30:31], 0
	v_mov_b64_e32 v[40:41], 0
	v_mov_b64_e32 v[42:43], 0
	v_mov_b64_e32 v[44:45], 0
	v_mov_b64_e32 v[46:47], 0
	v_mov_b64_e32 v[56:57], 0
	v_mov_b64_e32 v[58:59], 0
	v_mov_b64_e32 v[60:61], 0
	v_mov_b64_e32 v[62:63], 0
	v_mov_b64_e32 v[16:17], 0
	v_mov_b64_e32 v[18:19], 0
	v_mov_b64_e32 v[20:21], 0
	v_mov_b64_e32 v[22:23], 0
	v_mov_b64_e32 v[32:33], 0
	v_mov_b64_e32 v[34:35], 0
	v_mov_b64_e32 v[36:37], 0
	v_mov_b64_e32 v[38:39], 0
	v_mov_b64_e32 v[48:49], 0
	v_mov_b64_e32 v[50:51], 0
	v_mov_b64_e32 v[52:53], 0
	v_mov_b64_e32 v[54:55], 0
	v_mov_b64_e32 v[64:65], 0
	v_mov_b64_e32 v[66:67], 0
	v_mov_b64_e32 v[68:69], 0
	v_mov_b64_e32 v[70:71], 0
	v_mov_b64_e32 v[72:73], 0
	v_mov_b64_e32 v[74:75], 0
	v_mov_b64_e32 v[76:77], 0
	v_mov_b64_e32 v[78:79], 0
	v_mov_b64_e32 v[88:89], 0
	v_mov_b64_e32 v[90:91], 0
	v_mov_b64_e32 v[92:93], 0
	v_mov_b64_e32 v[94:95], 0
	v_mov_b64_e32 v[104:105], 0
	v_mov_b64_e32 v[106:107], 0
	v_mov_b64_e32 v[108:109], 0
	v_mov_b64_e32 v[110:111], 0
	v_mov_b64_e32 v[120:121], 0
	v_mov_b64_e32 v[122:123], 0
	v_mov_b64_e32 v[124:125], 0
	v_mov_b64_e32 v[126:127], 0
	v_mov_b64_e32 v[80:81], 0
	v_mov_b64_e32 v[82:83], 0
	v_mov_b64_e32 v[84:85], 0
	v_mov_b64_e32 v[86:87], 0
	v_mov_b64_e32 v[96:97], 0
	v_mov_b64_e32 v[98:99], 0
	v_mov_b64_e32 v[100:101], 0
	v_mov_b64_e32 v[102:103], 0
	v_mov_b64_e32 v[112:113], 0
	v_mov_b64_e32 v[114:115], 0
	v_mov_b64_e32 v[116:117], 0
	v_mov_b64_e32 v[118:119], 0
	v_mov_b64_e32 v[128:129], 0
	v_mov_b64_e32 v[130:131], 0
	v_mov_b64_e32 v[132:133], 0
	v_mov_b64_e32 v[134:135], 0
	s_mov_b64 s[42:43], 0x40000
	s_mov_b64 s[50:51], 0x60000
	s_mov_b64 s[52:53], 0x20080
	s_mov_b64 s[54:55], 0x40080
	s_mov_b64 s[58:59], 0x60080

;     ...
;         if (!(cs.kind == K_MG_B && cur.aux < 2))
; #pragma unroll
;         for (int a = 0; a < 2; ++a)
; #pragma unroll
;             for (int b = 0; b < 2; ++b)
; #pragma unroll
;                 for (int m = 0; m < 4; ++m)
; #pragma unroll
;                     for (int n = 0; n < 2; ++n) acc[a][b][m][n] = (f32x4){0.f, 0.f, 0.f, 0.f};
;         cur = nxt; cA = nA; cB = nB; ++ui;
.LBB0_1119:
	s_add_u32 s2, s16, 0x40080
	s_addc_u32 s3, s17, 0
	s_add_u32 s16, s18, 0x100
	v_mov_b64_e32 v[8:9], 0
	s_addc_u32 s17, s19, 0
	s_mov_b32 s18, -2
	v_mov_b64_e32 v[10:11], 0
	v_mov_b64_e32 v[16:17], 0
	v_mov_b64_e32 v[18:19], 0
	v_mov_b64_e32 v[24:25], 0
	v_mov_b64_e32 v[26:27], 0
	v_mov_b64_e32 v[32:33], 0
	v_mov_b64_e32 v[34:35], 0
	v_mov_b64_e32 v[40:41], 0
	v_mov_b64_e32 v[42:43], 0
	v_mov_b64_e32 v[48:49], 0
	v_mov_b64_e32 v[50:51], 0
	v_mov_b64_e32 v[56:57], 0
	v_mov_b64_e32 v[58:59], 0
	v_mov_b64_e32 v[64:65], 0
	v_mov_b64_e32 v[66:67], 0
	v_mov_b64_e32 v[12:13], 0
	v_mov_b64_e32 v[14:15], 0
	v_mov_b64_e32 v[20:21], 0
	v_mov_b64_e32 v[22:23], 0
	v_mov_b64_e32 v[28:29], 0
	v_mov_b64_e32 v[30:31], 0
	v_mov_b64_e32 v[36:37], 0
	v_mov_b64_e32 v[38:39], 0
	v_mov_b64_e32 v[44:45], 0
	v_mov_b64_e32 v[46:47], 0
	v_mov_b64_e32 v[52:53], 0
	v_mov_b64_e32 v[54:55], 0
	v_mov_b64_e32 v[60:61], 0
	v_mov_b64_e32 v[62:63], 0
	v_mov_b64_e32 v[68:69], 0
	v_mov_b64_e32 v[70:71], 0
	v_mov_b64_e32 v[72:73], 0
	v_mov_b64_e32 v[74:75], 0
	v_mov_b64_e32 v[80:81], 0
	v_mov_b64_e32 v[82:83], 0
	v_mov_b64_e32 v[88:89], 0
	v_mov_b64_e32 v[90:91], 0
	v_mov_b64_e32 v[96:97], 0
	v_mov_b64_e32 v[98:99], 0
	v_mov_b64_e32 v[104:105], 0
	v_mov_b64_e32 v[106:107], 0
	v_mov_b64_e32 v[112:113], 0
	v_mov_b64_e32 v[114:115], 0
	v_mov_b64_e32 v[120:121], 0
	v_mov_b64_e32 v[122:123], 0
	v_mov_b64_e32 v[128:129], 0
	v_mov_b64_e32 v[130:131], 0
	v_mov_b64_e32 v[76:77], 0
	v_mov_b64_e32 v[78:79], 0
	v_mov_b64_e32 v[84:85], 0
	v_mov_b64_e32 v[86:87], 0
	v_mov_b64_e32 v[92:93], 0
	v_mov_b64_e32 v[94:95], 0
	v_mov_b64_e32 v[100:101], 0
	v_mov_b64_e32 v[102:103], 0
	v_mov_b64_e32 v[108:109], 0
	v_mov_b64_e32 v[110:111], 0
	v_mov_b64_e32 v[116:117], 0
	v_mov_b64_e32 v[118:119], 0
	v_mov_b64_e32 v[124:125], 0
	v_mov_b64_e32 v[126:127], 0
	v_mov_b64_e32 v[132:133], 0
	v_mov_b64_e32 v[134:135], 0
	s_mov_b64 s[42:43], 0x40000
	s_mov_b64 s[50:51], 0x60000
	s_mov_b64 s[52:53], 0x20080
	s_mov_b64 s[54:55], 0x40080
	s_mov_b64 s[58:59], 0x60080

;     ...
;         if (!(cs.kind == K_MG_B && cur.aux < 2))
; #pragma unroll
;         for (int a = 0; a < 2; ++a)
; #pragma unroll
;             for (int b = 0; b < 2; ++b)
; #pragma unroll
;                 for (int m = 0; m < 4; ++m)
; #pragma unroll
;                     for (int n = 0; n < 2; ++n) acc[a][b][m][n] = (f32x4){0.f, 0.f, 0.f, 0.f};
;         cur = nxt; cA = nA; cB = nB; ++ui;
.LBB0_1184:
	s_add_u32 s2, s2, 0xb0080
	s_addc_u32 s3, s3, 0
	s_add_u32 s6, s6, 0x100
	s_waitcnt lgkmcnt(0)
	v_mov_b64_e32 v[8:9], 0
	s_addc_u32 s7, s7, 0
	s_mov_b32 s21, -2
	v_mov_b64_e32 v[10:11], 0
	v_mov_b64_e32 v[12:13], 0
	v_mov_b64_e32 v[14:15], 0
	v_mov_b64_e32 v[24:25], 0
	v_mov_b64_e32 v[26:27], 0
	v_mov_b64_e32 v[28:29], 0
	v_mov_b64_e32 v[30:31], 0
	v_mov_b64_e32 v[40:41], 0
	v_mov_b64_e32 v[42:43], 0
	v_mov_b64_e32 v[44:45], 0
	v_mov_b64_e32 v[46:47], 0
	v_mov_b64_e32 v[56:57], 0
	v_mov_b64_e32 v[58:59], 0
	v_mov_b64_e32 v[60:61], 0
	v_mov_b64_e32 v[62:63], 0
	v_mov_b64_e32 v[16:17], 0
	v_mov_b64_e32 v[18:19], 0
	v_mov_b64_e32 v[20:21], 0
	v_mov_b64_e32 v[22:23], 0
	v_mov_b64_e32 v[32:33], 0
	v_mov_b64_e32 v[34:35], 0
	v_mov_b64_e32 v[36:37], 0
	v_mov_b64_e32 v[38:39], 0
	v_mov_b64_e32 v[48:49], 0
	v_mov_b64_e32 v[50:51], 0
	v_mov_b64_e32 v[52:53], 0
	v_mov_b64_e32 v[54:55], 0
	v_mov_b64_e32 v[64:65], 0
	v_mov_b64_e32 v[66:67], 0
	v_mov_b64_e32 v[68:69], 0
	v_mov_b64_e32 v[70:71], 0
	v_mov_b64_e32 v[72:73], 0
	v_mov_b64_e32 v[74:75], 0
	v_mov_b64_e32 v[76:77], 0
	v_mov_b64_e32 v[78:79], 0
	v_mov_b64_e32 v[88:89], 0
	v_mov_b64_e32 v[90:91], 0
	v_mov_b64_e32 v[92:93], 0
	v_mov_b64_e32 v[94:95], 0
	v_mov_b64_e32 v[104:105], 0
	v_mov_b64_e32 v[106:107], 0
	v_mov_b64_e32 v[108:109], 0
	v_mov_b64_e32 v[110:111], 0
	v_mov_b64_e32 v[120:121], 0
	v_mov_b64_e32 v[122:123], 0
	v_mov_b64_e32 v[124:125], 0
	v_mov_b64_e32 v[126:127], 0
	v_mov_b64_e32 v[80:81], 0
	v_mov_b64_e32 v[82:83], 0
	v_mov_b64_e32 v[84:85], 0
	v_mov_b64_e32 v[86:87], 0
	v_mov_b64_e32 v[96:97], 0
	v_mov_b64_e32 v[98:99], 0
	v_mov_b64_e32 v[100:101], 0
	v_mov_b64_e32 v[102:103], 0
	v_mov_b64_e32 v[112:113], 0
	v_mov_b64_e32 v[114:115], 0
	v_mov_b64_e32 v[116:117], 0
	v_mov_b64_e32 v[118:119], 0
	v_mov_b64_e32 v[128:129], 0
	v_mov_b64_e32 v[130:131], 0
	v_mov_b64_e32 v[132:133], 0
	v_mov_b64_e32 v[134:135], 0
	s_mov_b64 s[52:53], 0xb0080
	s_mov_b64 s[54:55], 0x108080

;     ...
;         if (!(cs.kind == K_MG_B && cur.aux < 2))
; #pragma unroll
;         for (int a = 0; a < 2; ++a)
; #pragma unroll
;             for (int b = 0; b < 2; ++b)
; #pragma unroll
;                 for (int m = 0; m < 4; ++m)
; #pragma unroll
;                     for (int n = 0; n < 2; ++n) acc[a][b][m][n] = (f32x4){0.f, 0.f, 0.f, 0.f};
;         cur = nxt; cA = nA; cB = nB; ++ui;
.LBB0_1259:
	v_mov_b64_e32 v[8:9], 0
	s_mov_b64 s[18:19], 0
	s_mov_b64 s[14:15], -1
	s_mov_b64 s[16:17], 0
	v_mov_b64_e32 v[10:11], 0
	v_mov_b64_e32 v[12:13], 0
	v_mov_b64_e32 v[14:15], 0
	v_mov_b64_e32 v[16:17], 0
	v_mov_b64_e32 v[18:19], 0
	v_mov_b64_e32 v[24:25], 0
	v_mov_b64_e32 v[26:27], 0
	v_mov_b64_e32 v[32:33], 0
	v_mov_b64_e32 v[34:35], 0
	v_mov_b64_e32 v[40:41], 0
	v_mov_b64_e32 v[42:43], 0
	v_mov_b64_e32 v[48:49], 0
	v_mov_b64_e32 v[50:51], 0
	v_mov_b64_e32 v[56:57], 0
	v_mov_b64_e32 v[58:59], 0
	v_mov_b64_e32 v[20:21], 0
	v_mov_b64_e32 v[22:23], 0
	v_mov_b64_e32 v[28:29], 0
	v_mov_b64_e32 v[30:31], 0
	v_mov_b64_e32 v[36:37], 0
	v_mov_b64_e32 v[38:39], 0
	v_mov_b64_e32 v[44:45], 0
	v_mov_b64_e32 v[46:47], 0
	v_mov_b64_e32 v[52:53], 0
	v_mov_b64_e32 v[54:55], 0
	v_mov_b64_e32 v[60:61], 0
	v_mov_b64_e32 v[62:63], 0
	v_mov_b64_e32 v[64:65], 0
	v_mov_b64_e32 v[66:67], 0
	v_mov_b64_e32 v[68:69], 0
	v_mov_b64_e32 v[70:71], 0
	v_mov_b64_e32 v[72:73], 0
	v_mov_b64_e32 v[74:75], 0
	v_mov_b64_e32 v[76:77], 0
	v_mov_b64_e32 v[78:79], 0
	v_mov_b64_e32 v[80:81], 0
	v_mov_b64_e32 v[82:83], 0
	v_mov_b64_e32 v[88:89], 0
	v_mov_b64_e32 v[90:91], 0
	v_mov_b64_e32 v[96:97], 0
	v_mov_b64_e32 v[98:99], 0
	v_mov_b64_e32 v[104:105], 0
	v_mov_b64_e32 v[106:107], 0
	v_mov_b64_e32 v[112:113], 0
	v_mov_b64_e32 v[114:115], 0
	v_mov_b64_e32 v[120:121], 0
	v_mov_b64_e32 v[122:123], 0
	v_mov_b64_e32 v[84:85], 0
	v_mov_b64_e32 v[86:87], 0
	v_mov_b64_e32 v[92:93], 0
	v_mov_b64_e32 v[94:95], 0
	v_mov_b64_e32 v[100:101], 0
	v_mov_b64_e32 v[102:103], 0
	v_mov_b64_e32 v[108:109], 0
	v_mov_b64_e32 v[110:111], 0
	v_mov_b64_e32 v[116:117], 0
	v_mov_b64_e32 v[118:119], 0
	v_mov_b64_e32 v[124:125], 0
	v_mov_b64_e32 v[126:127], 0
	v_mov_b64_e32 v[128:129], 0
	v_mov_b64_e32 v[130:131], 0
	v_mov_b64_e32 v[132:133], 0
	v_mov_b64_e32 v[134:135], 0
	s_mov_b64 s[58:59], 0x10000

;     ...
;         if (!(cs.kind == K_MG_B && cur.aux < 2))
; #pragma unroll
;         for (int a = 0; a < 2; ++a)
; #pragma unroll
;             for (int b = 0; b < 2; ++b)
; #pragma unroll
;                 for (int m = 0; m < 4; ++m)
; #pragma unroll
;                     for (int n = 0; n < 2; ++n) acc[a][b][m][n] = (f32x4){0.f, 0.f, 0.f, 0.f};
;         cur = nxt; cA = nA; cB = nB; ++ui;
.LBB0_1282:
	s_add_u32 s2, s24, 0x40080
	s_addc_u32 s3, s25, 0
	s_add_u32 s22, s22, 0x100
	s_waitcnt lgkmcnt(0)
	v_mov_b64_e32 v[8:9], 0
	s_addc_u32 s23, s23, 0
	s_mov_b32 s24, -2
	v_mov_b64_e32 v[10:11], 0
	v_mov_b64_e32 v[12:13], 0
	v_mov_b64_e32 v[14:15], 0
	v_mov_b64_e32 v[24:25], 0
	v_mov_b64_e32 v[26:27], 0
	v_mov_b64_e32 v[28:29], 0
	v_mov_b64_e32 v[30:31], 0
	v_mov_b64_e32 v[40:41], 0
	v_mov_b64_e32 v[42:43], 0
	v_mov_b64_e32 v[44:45], 0
	v_mov_b64_e32 v[46:47], 0
	v_mov_b64_e32 v[56:57], 0
	v_mov_b64_e32 v[58:59], 0
	v_mov_b64_e32 v[60:61], 0
	v_mov_b64_e32 v[62:63], 0
	v_mov_b64_e32 v[16:17], 0
	v_mov_b64_e32 v[18:19], 0
	v_mov_b64_e32 v[20:21], 0
	v_mov_b64_e32 v[22:23], 0
	v_mov_b64_e32 v[32:33], 0
	v_mov_b64_e32 v[34:35], 0
	v_mov_b64_e32 v[36:37], 0
	v_mov_b64_e32 v[38:39], 0
	v_mov_b64_e32 v[48:49], 0
	v_mov_b64_e32 v[50:51], 0
	v_mov_b64_e32 v[52:53], 0
	v_mov_b64_e32 v[54:55], 0
	v_mov_b64_e32 v[64:65], 0
	v_mov_b64_e32 v[66:67], 0
	v_mov_b64_e32 v[68:69], 0
	v_mov_b64_e32 v[70:71], 0
	v_mov_b64_e32 v[72:73], 0
	v_mov_b64_e32 v[74:75], 0
	v_mov_b64_e32 v[76:77], 0
	v_mov_b64_e32 v[78:79], 0
	v_mov_b64_e32 v[88:89], 0
	v_mov_b64_e32 v[90:91], 0
	v_mov_b64_e32 v[92:93], 0
	v_mov_b64_e32 v[94:95], 0
	v_mov_b64_e32 v[104:105], 0
	v_mov_b64_e32 v[106:107], 0
	v_mov_b64_e32 v[108:109], 0
	v_mov_b64_e32 v[110:111], 0
	v_mov_b64_e32 v[120:121], 0
	v_mov_b64_e32 v[122:123], 0
	v_mov_b64_e32 v[124:125], 0
	v_mov_b64_e32 v[126:127], 0
	v_mov_b64_e32 v[80:81], 0
	v_mov_b64_e32 v[82:83], 0
	v_mov_b64_e32 v[84:85], 0
	v_mov_b64_e32 v[86:87], 0
	v_mov_b64_e32 v[96:97], 0
	v_mov_b64_e32 v[98:99], 0
	v_mov_b64_e32 v[100:101], 0
	v_mov_b64_e32 v[102:103], 0
	v_mov_b64_e32 v[112:113], 0
	v_mov_b64_e32 v[114:115], 0
	v_mov_b64_e32 v[116:117], 0
	v_mov_b64_e32 v[118:119], 0
	v_mov_b64_e32 v[128:129], 0
	v_mov_b64_e32 v[130:131], 0
	v_mov_b64_e32 v[132:133], 0
	v_mov_b64_e32 v[134:135], 0
	s_mov_b64 s[54:55], 0x40000
	s_mov_b64 s[58:59], 0x60000
	s_mov_b64 s[62:63], 0x20080
	s_mov_b64 s[64:65], 0x40080
	s_mov_b64 s[66:67], 0x60080
